# v22 + phase-4 epilogue keeps the whole x tile in flight: first 16 pieces staged through idle LDS by LDS-DMA, other 16 in registers
# speedup vs baseline: 1.0071x; 1.0063x over previous
.LBB0_1190:
	s_or_b64 exec, exec, s[30:31]
	v_and_b32_e32 v128, 15, v141
	s_lshl_b32 s4, s28, 8
	v_and_b32_e32 v129, 0x60, v142
	v_or3_b32 v128, v129, s4, v128
	v_ashrrev_i32_e32 v129, 2, v141
	v_and_b32_e32 v129, 0xffffffc0, v129
	v_lshl_add_u32 v129, s55, 8, v129
	v_lshrrev_b32_e32 v130, 2, v141
	v_and_or_b32 v130, v130, 12, v129
	v_ashrrev_i32_e32 v131, 31, v130
	v_lshlrev_b64 v[130:131], 2, v[130:131]
	v_mov_b32_e32 v228, v128
	v_ashrrev_i32_e32 v229, 31, v228
	v_lshlrev_b64 v[230:231], 12, v[228:229]
	v_lshl_add_u64 v[232:233], s[78:79], 0, v[230:231]
	v_lshl_add_u64 v[232:233], v[232:233], 0, s[24:25]
	v_lshl_add_u64 v[234:235], s[76:77], 0, v[230:231]
	v_cmp_gt_i32_e32 vcc, s49, v228
	v_lshl_add_u64 v[220:221], s[26:27], 0, v[230:231]
	v_lshl_add_u64 v[220:221], v[220:221], 0, v[130:131]
	v_cndmask_b32_e32 v232, v232, v234, vcc
	v_cndmask_b32_e32 v233, v233, v235, vcc
	v_lshl_add_u64 v[212:213], v[232:233], 0, v[130:131]
	v_or_b32_e32 v228, 0x10, v128
	v_ashrrev_i32_e32 v229, 31, v228
	v_lshlrev_b64 v[230:231], 12, v[228:229]
	v_lshl_add_u64 v[232:233], s[78:79], 0, v[230:231]
	v_lshl_add_u64 v[232:233], v[232:233], 0, s[24:25]
	v_lshl_add_u64 v[234:235], s[76:77], 0, v[230:231]
	v_cmp_gt_i32_e32 vcc, s49, v228
	v_lshl_add_u64 v[222:223], s[26:27], 0, v[230:231]
	v_lshl_add_u64 v[222:223], v[222:223], 0, v[130:131]
	v_cndmask_b32_e32 v232, v232, v234, vcc
	v_cndmask_b32_e32 v233, v233, v235, vcc
	v_lshl_add_u64 v[214:215], v[232:233], 0, v[130:131]
	v_or_b32_e32 v228, 0x80, v128
	v_ashrrev_i32_e32 v229, 31, v228
	v_lshlrev_b64 v[230:231], 12, v[228:229]
	v_lshl_add_u64 v[232:233], s[78:79], 0, v[230:231]
	v_lshl_add_u64 v[232:233], v[232:233], 0, s[24:25]
	v_lshl_add_u64 v[234:235], s[76:77], 0, v[230:231]
	v_cmp_gt_i32_e32 vcc, s49, v228
	v_lshl_add_u64 v[224:225], s[26:27], 0, v[230:231]
	v_lshl_add_u64 v[224:225], v[224:225], 0, v[130:131]
	v_cndmask_b32_e32 v232, v232, v234, vcc
	v_cndmask_b32_e32 v233, v233, v235, vcc
	v_lshl_add_u64 v[216:217], v[232:233], 0, v[130:131]
	v_or_b32_e32 v228, 0x90, v128
	v_ashrrev_i32_e32 v229, 31, v228
	v_lshlrev_b64 v[230:231], 12, v[228:229]
	v_lshl_add_u64 v[232:233], s[78:79], 0, v[230:231]
	v_lshl_add_u64 v[232:233], v[232:233], 0, s[24:25]
	v_lshl_add_u64 v[234:235], s[76:77], 0, v[230:231]
	v_cmp_gt_i32_e32 vcc, s49, v228
	v_lshl_add_u64 v[226:227], s[26:27], 0, v[230:231]
	v_lshl_add_u64 v[226:227], v[226:227], 0, v[130:131]
	v_cndmask_b32_e32 v232, v232, v234, vcc
	v_cndmask_b32_e32 v233, v233, v235, vcc
	v_lshl_add_u64 v[218:219], v[232:233], 0, v[130:131]
	v_readfirstlane_b32 s40, v192
	v_and_b32_e32 v143, 63, v192
	s_lshr_b32 s40, s40, 6
	v_lshlrev_b32_e32 v143, 4, v143
	s_lshl_b32 s40, s40, 14
	s_add_u32 s40, s40, 16
	v_add_u32_e32 v143, s40, v143
	s_movk_i32 s4, 0x0
	v_lshl_add_u64 v[132:133], v[212:213], 0, s[4:5]
	s_add_u32 s41, s40, 0x0
	s_mov_b32 m0, s41
	s_nop 0
	global_load_lds_dwordx4 v[132:133], off
	s_movk_i32 s4, 0x40
	v_lshl_add_u64 v[132:133], v[212:213], 0, s[4:5]
	s_add_u32 s41, s40, 0x400
	s_mov_b32 m0, s41
	s_nop 0
	global_load_lds_dwordx4 v[132:133], off
	s_movk_i32 s4, 0x80
	v_lshl_add_u64 v[132:133], v[212:213], 0, s[4:5]
	s_add_u32 s41, s40, 0x800
	s_mov_b32 m0, s41
	s_nop 0
	global_load_lds_dwordx4 v[132:133], off
	s_movk_i32 s4, 0xc0
	v_lshl_add_u64 v[132:133], v[212:213], 0, s[4:5]
	s_add_u32 s41, s40, 0xc00
	s_mov_b32 m0, s41
	s_nop 0
	global_load_lds_dwordx4 v[132:133], off
	s_movk_i32 s4, 0x200
	v_lshl_add_u64 v[132:133], v[212:213], 0, s[4:5]
	s_add_u32 s41, s40, 0x1000
	s_mov_b32 m0, s41
	s_nop 0
	global_load_lds_dwordx4 v[132:133], off
	s_movk_i32 s4, 0x240
	v_lshl_add_u64 v[132:133], v[212:213], 0, s[4:5]
	s_add_u32 s41, s40, 0x1400
	s_mov_b32 m0, s41
	s_nop 0
	global_load_lds_dwordx4 v[132:133], off
	s_movk_i32 s4, 0x280
	v_lshl_add_u64 v[132:133], v[212:213], 0, s[4:5]
	s_add_u32 s41, s40, 0x1800
	s_mov_b32 m0, s41
	s_nop 0
	global_load_lds_dwordx4 v[132:133], off
	s_movk_i32 s4, 0x2c0
	v_lshl_add_u64 v[132:133], v[212:213], 0, s[4:5]
	s_add_u32 s41, s40, 0x1c00
	s_mov_b32 m0, s41
	s_nop 0
	global_load_lds_dwordx4 v[132:133], off
	s_movk_i32 s4, 0x0
	v_lshl_add_u64 v[132:133], v[214:215], 0, s[4:5]
	s_add_u32 s41, s40, 0x2000
	s_mov_b32 m0, s41
	s_nop 0
	global_load_lds_dwordx4 v[132:133], off
	s_movk_i32 s4, 0x40
	v_lshl_add_u64 v[132:133], v[214:215], 0, s[4:5]
	s_add_u32 s41, s40, 0x2400
	s_mov_b32 m0, s41
	s_nop 0
	global_load_lds_dwordx4 v[132:133], off
	s_movk_i32 s4, 0x80
	v_lshl_add_u64 v[132:133], v[214:215], 0, s[4:5]
	s_add_u32 s41, s40, 0x2800
	s_mov_b32 m0, s41
	s_nop 0
	global_load_lds_dwordx4 v[132:133], off
	s_movk_i32 s4, 0xc0
	v_lshl_add_u64 v[132:133], v[214:215], 0, s[4:5]
	s_add_u32 s41, s40, 0x2c00
	s_mov_b32 m0, s41
	s_nop 0
	global_load_lds_dwordx4 v[132:133], off
	s_movk_i32 s4, 0x200
	v_lshl_add_u64 v[132:133], v[214:215], 0, s[4:5]
	s_add_u32 s41, s40, 0x3000
	s_mov_b32 m0, s41
	s_nop 0
	global_load_lds_dwordx4 v[132:133], off
	s_movk_i32 s4, 0x240
	v_lshl_add_u64 v[132:133], v[214:215], 0, s[4:5]
	s_add_u32 s41, s40, 0x3400
	s_mov_b32 m0, s41
	s_nop 0
	global_load_lds_dwordx4 v[132:133], off
	s_movk_i32 s4, 0x280
	v_lshl_add_u64 v[132:133], v[214:215], 0, s[4:5]
	s_add_u32 s41, s40, 0x3800
	s_mov_b32 m0, s41
	s_nop 0
	global_load_lds_dwordx4 v[132:133], off
	s_movk_i32 s4, 0x2c0
	v_lshl_add_u64 v[132:133], v[214:215], 0, s[4:5]
	s_add_u32 s41, s40, 0x3c00
	s_mov_b32 m0, s41
	s_nop 0
	global_load_lds_dwordx4 v[132:133], off
	global_load_dwordx4 v[144:147], v[216:217], off
	global_load_dwordx4 v[148:151], v[216:217], off offset:64
	global_load_dwordx4 v[152:155], v[216:217], off offset:128
	global_load_dwordx4 v[156:159], v[216:217], off offset:192
	global_load_dwordx4 v[160:163], v[216:217], off offset:512
	global_load_dwordx4 v[164:167], v[216:217], off offset:576
	global_load_dwordx4 v[168:171], v[216:217], off offset:640
	global_load_dwordx4 v[172:175], v[216:217], off offset:704
	global_load_dwordx4 v[176:179], v[218:219], off
	global_load_dwordx4 v[180:183], v[218:219], off offset:64
	global_load_dwordx4 v[184:187], v[218:219], off offset:128
	global_load_dwordx4 v[188:191], v[218:219], off offset:192
	global_load_dwordx4 v[196:199], v[218:219], off offset:512
	global_load_dwordx4 v[200:203], v[218:219], off offset:576
	global_load_dwordx4 v[204:207], v[218:219], off offset:640
	global_load_dwordx4 v[208:211], v[218:219], off offset:704
	s_waitcnt vmcnt(31)
	ds_read_b128 v[136:139], v143
	s_waitcnt lgkmcnt(0)
	v_pk_add_f32 v[116:117], v[116:117], v[136:137]
	v_pk_add_f32 v[118:119], v[118:119], v[138:139]
	global_store_dwordx4 v[220:221], v[116:119], off
	s_waitcnt vmcnt(31)
	ds_read_b128 v[136:139], v143 offset:1024
	s_waitcnt lgkmcnt(0)
	v_pk_add_f32 v[108:109], v[108:109], v[136:137]
	v_pk_add_f32 v[110:111], v[110:111], v[138:139]
	global_store_dwordx4 v[220:221], v[108:111], off offset:64
	s_waitcnt vmcnt(31)
	ds_read_b128 v[136:139], v143 offset:2048
	s_waitcnt lgkmcnt(0)
	v_pk_add_f32 v[104:105], v[104:105], v[136:137]
	v_pk_add_f32 v[106:107], v[106:107], v[138:139]
	global_store_dwordx4 v[220:221], v[104:107], off offset:128
	s_waitcnt vmcnt(31)
	ds_read_b128 v[136:139], v143 offset:3072
	s_waitcnt lgkmcnt(0)
	v_pk_add_f32 v[100:101], v[100:101], v[136:137]
	v_pk_add_f32 v[102:103], v[102:103], v[138:139]
	global_store_dwordx4 v[220:221], v[100:103], off offset:192
	s_waitcnt vmcnt(31)
	ds_read_b128 v[136:139], v143 offset:4096
	s_waitcnt lgkmcnt(0)
	v_pk_add_f32 v[124:125], v[124:125], v[136:137]
	v_pk_add_f32 v[126:127], v[126:127], v[138:139]
	global_store_dwordx4 v[220:221], v[124:127], off offset:512
	s_waitcnt vmcnt(31)
	ds_read_b128 v[136:139], v143 offset:5120
	s_waitcnt lgkmcnt(0)
	v_pk_add_f32 v[120:121], v[120:121], v[136:137]
	v_pk_add_f32 v[122:123], v[122:123], v[138:139]
	global_store_dwordx4 v[220:221], v[120:123], off offset:576
	s_waitcnt vmcnt(31)
	ds_read_b128 v[136:139], v143 offset:6144
	s_waitcnt lgkmcnt(0)
	v_pk_add_f32 v[112:113], v[112:113], v[136:137]
	v_pk_add_f32 v[114:115], v[114:115], v[138:139]
	global_store_dwordx4 v[220:221], v[112:115], off offset:640
	s_waitcnt vmcnt(31)
	ds_read_b128 v[136:139], v143 offset:7168
	s_waitcnt lgkmcnt(0)
	v_pk_add_f32 v[96:97], v[96:97], v[136:137]
	v_pk_add_f32 v[98:99], v[98:99], v[138:139]
	global_store_dwordx4 v[220:221], v[96:99], off offset:704
	s_waitcnt vmcnt(31)
	ds_read_b128 v[136:139], v143 offset:8192
	s_waitcnt lgkmcnt(0)
	v_pk_add_f32 v[84:85], v[84:85], v[136:137]
	v_pk_add_f32 v[86:87], v[86:87], v[138:139]
	global_store_dwordx4 v[222:223], v[84:87], off
	s_waitcnt vmcnt(31)
	ds_read_b128 v[136:139], v143 offset:9216
	s_waitcnt lgkmcnt(0)
	v_pk_add_f32 v[76:77], v[76:77], v[136:137]
	v_pk_add_f32 v[78:79], v[78:79], v[138:139]
	global_store_dwordx4 v[222:223], v[76:79], off offset:64
	s_waitcnt vmcnt(31)
	ds_read_b128 v[136:139], v143 offset:10240
	s_waitcnt lgkmcnt(0)
	v_pk_add_f32 v[72:73], v[72:73], v[136:137]
	v_pk_add_f32 v[74:75], v[74:75], v[138:139]
	global_store_dwordx4 v[222:223], v[72:75], off offset:128
	s_waitcnt vmcnt(31)
	ds_read_b128 v[136:139], v143 offset:11264
	s_waitcnt lgkmcnt(0)
	v_pk_add_f32 v[68:69], v[68:69], v[136:137]
	v_pk_add_f32 v[70:71], v[70:71], v[138:139]
	global_store_dwordx4 v[222:223], v[68:71], off offset:192
	s_waitcnt vmcnt(31)
	ds_read_b128 v[136:139], v143 offset:12288
	s_waitcnt lgkmcnt(0)
	v_pk_add_f32 v[92:93], v[92:93], v[136:137]
	v_pk_add_f32 v[94:95], v[94:95], v[138:139]
	global_store_dwordx4 v[222:223], v[92:95], off offset:512
	s_waitcnt vmcnt(31)
	ds_read_b128 v[136:139], v143 offset:13312
	s_waitcnt lgkmcnt(0)
	v_pk_add_f32 v[88:89], v[88:89], v[136:137]
	v_pk_add_f32 v[90:91], v[90:91], v[138:139]
	global_store_dwordx4 v[222:223], v[88:91], off offset:576
	s_waitcnt vmcnt(31)
	ds_read_b128 v[136:139], v143 offset:14336
	s_waitcnt lgkmcnt(0)
	v_pk_add_f32 v[80:81], v[80:81], v[136:137]
	v_pk_add_f32 v[82:83], v[82:83], v[138:139]
	global_store_dwordx4 v[222:223], v[80:83], off offset:640
	s_waitcnt vmcnt(31)
	ds_read_b128 v[136:139], v143 offset:15360
	s_waitcnt lgkmcnt(0)
	v_pk_add_f32 v[64:65], v[64:65], v[136:137]
	v_pk_add_f32 v[66:67], v[66:67], v[138:139]
	global_store_dwordx4 v[222:223], v[64:67], off offset:704
	s_barrier
	s_waitcnt vmcnt(31)
	v_pk_add_f32 v[60:61], v[60:61], v[144:145]
	v_pk_add_f32 v[62:63], v[62:63], v[146:147]
	global_store_dwordx4 v[224:225], v[60:63], off
	s_waitcnt vmcnt(31)
	v_pk_add_f32 v[52:53], v[52:53], v[148:149]
	v_pk_add_f32 v[54:55], v[54:55], v[150:151]
	global_store_dwordx4 v[224:225], v[52:55], off offset:64
	s_waitcnt vmcnt(31)
	v_pk_add_f32 v[44:45], v[44:45], v[152:153]
	v_pk_add_f32 v[46:47], v[46:47], v[154:155]
	global_store_dwordx4 v[224:225], v[44:47], off offset:128
	s_waitcnt vmcnt(31)
	v_pk_add_f32 v[36:37], v[36:37], v[156:157]
	v_pk_add_f32 v[38:39], v[38:39], v[158:159]
	global_store_dwordx4 v[224:225], v[36:39], off offset:192
	s_waitcnt vmcnt(31)
	v_pk_add_f32 v[56:57], v[56:57], v[160:161]
	v_pk_add_f32 v[58:59], v[58:59], v[162:163]
	global_store_dwordx4 v[224:225], v[56:59], off offset:512
	s_waitcnt vmcnt(31)
	v_pk_add_f32 v[48:49], v[48:49], v[164:165]
	v_pk_add_f32 v[50:51], v[50:51], v[166:167]
	global_store_dwordx4 v[224:225], v[48:51], off offset:576
	s_waitcnt vmcnt(31)
	v_pk_add_f32 v[40:41], v[40:41], v[168:169]
	v_pk_add_f32 v[42:43], v[42:43], v[170:171]
	global_store_dwordx4 v[224:225], v[40:43], off offset:640
	s_waitcnt vmcnt(31)
	v_pk_add_f32 v[32:33], v[32:33], v[172:173]
	v_pk_add_f32 v[34:35], v[34:35], v[174:175]
	global_store_dwordx4 v[224:225], v[32:35], off offset:704
	s_waitcnt vmcnt(31)
	v_pk_add_f32 v[28:29], v[28:29], v[176:177]
	v_pk_add_f32 v[30:31], v[30:31], v[178:179]
	global_store_dwordx4 v[226:227], v[28:31], off
	s_waitcnt vmcnt(31)
	v_pk_add_f32 v[20:21], v[20:21], v[180:181]
	v_pk_add_f32 v[22:23], v[22:23], v[182:183]
	global_store_dwordx4 v[226:227], v[20:23], off offset:64
	s_waitcnt vmcnt(31)
	v_pk_add_f32 v[12:13], v[12:13], v[184:185]
	v_pk_add_f32 v[14:15], v[14:15], v[186:187]
	global_store_dwordx4 v[226:227], v[12:15], off offset:128
	s_waitcnt vmcnt(31)
	v_pk_add_f32 v[4:5], v[4:5], v[188:189]
	v_pk_add_f32 v[6:7], v[6:7], v[190:191]
	global_store_dwordx4 v[226:227], v[4:7], off offset:192
	s_waitcnt vmcnt(31)
	v_pk_add_f32 v[24:25], v[24:25], v[196:197]
	v_pk_add_f32 v[26:27], v[26:27], v[198:199]
	global_store_dwordx4 v[226:227], v[24:27], off offset:512
	s_waitcnt vmcnt(31)
	v_pk_add_f32 v[16:17], v[16:17], v[200:201]
	v_pk_add_f32 v[18:19], v[18:19], v[202:203]
	global_store_dwordx4 v[226:227], v[16:19], off offset:576
	s_waitcnt vmcnt(31)
	v_pk_add_f32 v[8:9], v[8:9], v[204:205]
	v_pk_add_f32 v[10:11], v[10:11], v[206:207]
	global_store_dwordx4 v[226:227], v[8:11], off offset:640
	s_waitcnt vmcnt(31)
	v_pk_add_f32 v[0:1], v[0:1], v[208:209]
	v_pk_add_f32 v[2:3], v[2:3], v[210:211]
	global_store_dwordx4 v[226:227], v[0:3], off offset:704
	s_mov_b64 s[26:27], exec
	v_readlane_b32 s28, v255, 10
	v_readlane_b32 s29, v255, 11
	s_and_b64 s[28:29], s[26:27], s[28:29]
	s_mov_b64 exec, s[28:29]
	s_cbranch_execz .LBB0_1183
	s_mov_b64 s[28:29], exec
	v_mbcnt_lo_u32_b32 v0, s28, 0
	v_mbcnt_hi_u32_b32 v0, s29, v0
	v_cmp_eq_u32_e32 vcc, 0, v0
	s_and_b64 s[30:31], exec, vcc
	s_mov_b64 exec, s[30:31]
	s_cbranch_execz .LBB0_1183
	s_bcnt1_i32_b64 s4, s[28:29]
	v_mov_b32_e32 v0, s4
	global_atomic_add v140, v0, s[0:1]
	s_branch .LBB0_1183
